# nt (non-temporal) hint on the streaming z (gemm_in) and act (gate-up) output stores so they stop displacing A/B tiles from L2
# speedup vs baseline: 1.2918x; 1.0174x over previous
.LBB0_49:
	v_lshrrev_b32_e32 v2, 6, v134
	v_lshlrev_b32_e32 v3, 4, v134
	v_bfe_u32 v0, v134, 3, 3
	v_and_b32_e32 v3, 0x70, v3
	v_and_b32_e32 v4, 8, v2
	v_or3_b32 v135, v3, v4, v0
	v_ashrrev_i32_e32 v0, 7, v134
	v_bfi_b32 v136, -8, v0, v2
	v_mul_u32_u24_e32 v0, 0x5a000, v135
	v_mov_b64_e32 v[2:3], s[58:59]
	s_mov_b32 s2, 0xb4000
	v_lshlrev_b32_e32 v0, 1, v0
	v_mad_i64_i32 v[6:7], s[2:3], v136, s2, v[2:3]
	v_mov_b32_e32 v2, v163
	v_lshl_add_u64 v[4:5], s[78:79], 0, v[0:1]
	s_nop 0
	v_ashrrev_i32_e32 v3, 3, v2
	v_lshlrev_b32_e32 v0, 4, v2
	v_mad_i64_i32 v[4:5], s[2:3], v3, s38, v[4:5]
	v_and_b32_e32 v0, 0x70, v0
	v_lshl_add_u64 v[130:131], v[4:5], 0, v[0:1]
	v_add_co_u32_e32 v32, vcc, s39, v130
	v_mad_i64_i32 v[4:5], s[2:3], v3, s38, v[6:7]
	v_lshl_add_u64 v[132:133], v[4:5], 0, v[0:1]
	v_and_b32_e32 v110, 7, v163
	v_bfe_u32 v111, v163, 4, 3
	v_xor_b32_e32 v111, v111, v110
	v_sub_u32_e32 v111, v111, v110
	v_lshlrev_b32_e32 v111, 4, v111
	v_lshrrev_b32_e32 v112, 6, v163
	v_lshlrev_b32_e32 v112, 10, v112
	v_readfirstlane_b32 s2, v130
	v_readfirstlane_b32 s3, v131
	v_readfirstlane_b32 s4, v132
	v_readfirstlane_b32 s5, v133
	v_readfirstlane_b32 s6, v112
	s_nop 3
	v_subrev_u32_e32 v98, s2, v130
	v_subrev_u32_e32 v102, s4, v132
	v_add_u32_e32 v98, v98, v111
	v_add_u32_e32 v102, v102, v111
	v_add_u32_e32 v99, 0x2d000, v98
	v_add_u32_e32 v103, 0x2d000, v102
	v_add_u32_e32 v100, 0x5a000, v98
	v_add_u32_e32 v104, 0x5a000, v102
	v_add_u32_e32 v101, 0x87000, v98
	v_add_u32_e32 v105, 0x87000, v102
	v_lshlrev_b32_e32 v110, 3, v163
	v_lshlrev_b32_e32 v111, 7, v163
	v_and_b32_e32 v112, 0x2000, v111
	v_and_b32_e32 v111, 0x780, v111
	v_and_b32_e32 v107, 64, v110
	v_xor_b32_e32 v110, v110, v163
	v_and_b32_e32 v110, 48, v110
	v_or3_b32 v110, v111, v107, v110
	v_lshlrev_b32_e32 v111, 6, v163
	v_and_b32_e32 v111, 0xffffe000, v111
	v_or_b32_e32 v108, v110, v112
	v_or_b32_e32 v106, v110, v111
	v_xor_b32_e32 v107, 64, v106
	v_xor_b32_e32 v109, 64, v108
	s_mov_b32 m0, s6
	s_nop 0
	global_load_lds_dwordx4 v98, s[2:3]
	s_add_u32 m0, s6, 0x1000
	s_nop 0
	global_load_lds_dwordx4 v99, s[2:3]
	s_add_u32 m0, s6, 0x2000
	s_nop 0
	global_load_lds_dwordx4 v100, s[2:3]
	s_add_u32 m0, s6, 0x3000
	s_nop 0
	global_load_lds_dwordx4 v101, s[2:3]
	s_add_u32 m0, s6, 0x4000
	s_nop 0
	global_load_lds_dwordx4 v102, s[4:5]
	s_add_u32 m0, s6, 0x5000
	s_nop 0
	global_load_lds_dwordx4 v103, s[4:5]
	s_add_u32 m0, s6, 0x6000
	s_nop 0
	global_load_lds_dwordx4 v104, s[4:5]
	s_add_u32 m0, s6, 0x7000
	s_nop 0
	global_load_lds_dwordx4 v105, s[4:5]
	s_waitcnt vmcnt(0)
	s_add_u32 s2, s2, 0x80
	s_addc_u32 s3, s3, 0
	s_add_u32 s4, s4, 0x80
	s_addc_u32 s5, s5, 0
	s_barrier
	s_add_u32 m0, s6, 0x8000
	ds_read_b128 v[142:145], v106
	ds_read_b128 v[158:161], v108 offset:16384
	s_nop 0
	global_load_lds_dwordx4 v98, s[2:3]
	s_add_u32 m0, s6, 0x9000
	ds_read_b128 v[182:185], v108 offset:18432
	ds_read_b128 v[186:189], v108 offset:20480
	s_nop 0
	global_load_lds_dwordx4 v99, s[2:3]
	s_add_u32 m0, s6, 0xa000
	ds_read_b128 v[206:209], v108 offset:22528
	ds_read_b128 v[146:149], v106 offset:2048
	s_nop 0
	global_load_lds_dwordx4 v100, s[2:3]
	s_add_u32 m0, s6, 0xb000
	ds_read_b128 v[150:153], v106 offset:4096
	ds_read_b128 v[154:157], v106 offset:6144
	s_nop 0
	global_load_lds_dwordx4 v101, s[2:3]
	s_add_u32 m0, s6, 0xc000
	s_nop 0
	global_load_lds_dwordx4 v102, s[4:5]
	s_add_u32 m0, s6, 0xd000
	s_nop 0
	global_load_lds_dwordx4 v103, s[4:5]
	s_add_u32 m0, s6, 0xe000
	s_nop 0
	global_load_lds_dwordx4 v104, s[4:5]
	s_add_u32 m0, s6, 0xf000
	s_nop 0
	global_load_lds_dwordx4 v105, s[4:5]
	s_add_u32 s2, s2, 0x80
	s_addc_u32 s3, s3, 0
	s_add_u32 s4, s4, 0x80
	s_addc_u32 s5, s5, 0
	s_waitcnt lgkmcnt(0)
	v_mfma_f32_16x16x32_bf16 v[94:97], v[158:161], v[142:145], 0
	ds_read_b128 v[34:37], v107
	ds_read_b128 v[54:57], v109 offset:16384
	v_mfma_f32_16x16x32_bf16 v[90:93], v[182:185], v[142:145], 0
	v_mfma_f32_16x16x32_bf16 v[86:89], v[186:189], v[142:145], 0
	ds_read_b128 v[62:65], v109 offset:18432
	ds_read_b128 v[66:69], v109 offset:20480
	v_mfma_f32_16x16x32_bf16 v[82:85], v[206:209], v[142:145], 0
	v_mfma_f32_16x16x32_bf16 v[74:77], v[158:161], v[146:149], 0
	ds_read_b128 v[78:81], v109 offset:22528
	ds_read_b128 v[38:41], v107 offset:2048
	v_mfma_f32_16x16x32_bf16 v[70:73], v[182:185], v[146:149], 0
	v_mfma_f32_16x16x32_bf16 v[58:61], v[186:189], v[146:149], 0
	ds_read_b128 v[46:49], v107 offset:4096
	ds_read_b128 v[50:53], v107 offset:6144
	v_mfma_f32_16x16x32_bf16 v[42:45], v[206:209], v[146:149], 0
	v_mfma_f32_16x16x32_bf16 v[30:33], v[158:161], v[150:153], 0
	v_mfma_f32_16x16x32_bf16 v[26:29], v[182:185], v[150:153], 0
	v_mfma_f32_16x16x32_bf16 v[22:25], v[186:189], v[150:153], 0
	v_mfma_f32_16x16x32_bf16 v[18:21], v[206:209], v[150:153], 0
	v_mfma_f32_16x16x32_bf16 v[14:17], v[158:161], v[154:157], 0
	v_mfma_f32_16x16x32_bf16 v[10:13], v[182:185], v[154:157], 0
	v_mfma_f32_16x16x32_bf16 v[6:9], v[186:189], v[154:157], 0
	v_mfma_f32_16x16x32_bf16 v[2:5], v[206:209], v[154:157], 0
	s_waitcnt vmcnt(0) lgkmcnt(0)
	s_barrier
	s_movk_i32 s7, 21

.LBB0_58:
	s_waitcnt vmcnt(6)
	v_mul_f32_e32 v62, 0xbfb8aa3b, v92
	v_exp_f32_e32 v62, v62
	v_mov_b32_e32 v0, v163
	v_mov_b32_e32 v59, v163
	v_add_f32_e32 v62, 1.0, v62
	v_and_b32_e32 v60, 15, v0
	v_lshrrev_b32_e32 v59, 1, v59
	v_lshrrev_b32_e32 v0, 2, v0
	v_rcp_f32_e32 v62, v62
	v_lshlrev_b32_e32 v58, 6, v136
	v_and_b32_e32 v61, 32, v59
	v_and_b32_e32 v0, 12, v0
	v_or3_b32 v0, v0, v61, v58
	s_mov_b32 s2, 0xfffffc0
	v_and_or_b32 v59, v59, s2, v60
	v_lshlrev_b32_e32 v0, 1, v0
	v_lshlrev_b32_e32 v60, 7, v136
	v_sub_u32_e32 v0, v0, v60
	v_mul_f32_e32 v60, 0xbfb8aa3b, v90
	v_mul_f32_e32 v61, 0xbfb8aa3b, v91
	v_mul_f32_e32 v62, v92, v62
	v_exp_f32_e32 v60, v60
	v_exp_f32_e32 v61, v61
	v_mul_f32_e32 v63, v88, v62
	v_mul_f32_e32 v62, 0xbfb8aa3b, v93
	v_exp_f32_e32 v62, v62
	v_add_f32_e32 v60, 1.0, v60
	v_add_f32_e32 v61, 1.0, v61
	v_rcp_f32_e32 v60, v60
	v_rcp_f32_e32 v61, v61
	v_add_f32_e32 v62, 1.0, v62
	v_rcp_f32_e32 v62, v62
	v_mul_f32_e32 v60, v90, v60
	v_mul_f32_e32 v61, v91, v61
	v_mul_f32_e32 v60, v86, v60
	v_mul_f32_e32 v61, v87, v61
	v_mul_f32_e32 v62, v93, v62
	s_movk_i32 s4, 0x90
	v_mul_f32_e32 v64, v89, v62
	v_cvt_pk_bf16_f32 v62, v60, v61
	v_mad_u64_u32 v[60:61], s[2:3], v59, s4, v[0:1]
	v_mul_f32_e32 v0, 0xbfb8aa3b, v54
	v_exp_f32_e32 v0, v0
	v_cvt_pk_bf16_f32 v63, v63, v64
	v_ashrrev_i32_e32 v59, 31, v58
	v_add_f32_e32 v0, 1.0, v0
	v_rcp_f32_e32 v0, v0
	s_nop 0
	v_mul_f32_e32 v0, v54, v0
	v_mul_f32_e32 v0, v50, v0
	v_mul_f32_e32 v50, 0xbfb8aa3b, v55
	v_exp_f32_e32 v50, v50
	s_nop 0
	v_add_f32_e32 v50, 1.0, v50
	v_rcp_f32_e32 v50, v50
	s_nop 0
	v_mul_f32_e32 v50, v55, v50
	v_mul_f32_e32 v50, v51, v50
	v_cvt_pk_bf16_f32 v50, v0, v50
	v_mul_f32_e32 v0, 0xbfb8aa3b, v46
	v_exp_f32_e32 v0, v0
	v_mul_f32_e32 v51, 0xbfb8aa3b, v56
	v_exp_f32_e32 v51, v51
	v_add_f32_e32 v0, 1.0, v0
	v_rcp_f32_e32 v0, v0
	v_add_f32_e32 v51, 1.0, v51
	v_rcp_f32_e32 v51, v51
	v_mul_f32_e32 v0, v46, v0
	v_mul_f32_e32 v0, v42, v0
	v_mul_f32_e32 v42, 0xbfb8aa3b, v47
	v_exp_f32_e32 v42, v42
	v_mul_f32_e32 v51, v56, v51
	v_mul_f32_e32 v51, v52, v51
	v_mul_f32_e32 v52, 0xbfb8aa3b, v57
	v_add_f32_e32 v42, 1.0, v42
	v_rcp_f32_e32 v42, v42
	v_exp_f32_e32 v52, v52
	v_mul_f32_e32 v42, v47, v42
	v_mul_f32_e32 v42, v43, v42
	v_cvt_pk_bf16_f32 v42, v0, v42
	v_mul_f32_e32 v0, 0xbfb8aa3b, v38
	v_exp_f32_e32 v0, v0
	v_mul_f32_e32 v43, 0xbfb8aa3b, v48
	v_exp_f32_e32 v43, v43
	v_add_f32_e32 v52, 1.0, v52
	v_add_f32_e32 v0, 1.0, v0
	v_rcp_f32_e32 v0, v0
	v_add_f32_e32 v43, 1.0, v43
	v_rcp_f32_e32 v43, v43
	v_rcp_f32_e32 v52, v52
	v_mul_f32_e32 v0, v38, v0
	v_mul_f32_e32 v0, v34, v0
	v_mul_f32_e32 v34, 0xbfb8aa3b, v39
	v_exp_f32_e32 v34, v34
	v_mul_f32_e32 v43, v48, v43
	v_mul_f32_e32 v43, v44, v43
	v_mul_f32_e32 v44, 0xbfb8aa3b, v49
	v_add_f32_e32 v34, 1.0, v34
	v_rcp_f32_e32 v34, v34
	v_exp_f32_e32 v44, v44
	v_mul_f32_e32 v52, v57, v52
	v_mul_f32_e32 v52, v53, v52
	v_mul_f32_e32 v34, v39, v34
	v_mul_f32_e32 v34, v35, v34
	v_mul_f32_e32 v35, 0xbfb8aa3b, v40
	v_exp_f32_e32 v35, v35
	v_add_f32_e32 v44, 1.0, v44
	v_rcp_f32_e32 v44, v44
	v_cvt_pk_bf16_f32 v34, v0, v34
	v_add_f32_e32 v35, 1.0, v35
	v_rcp_f32_e32 v35, v35
	v_mul_f32_e32 v44, v49, v44
	v_add_u32_e32 v0, 0x800, v60
	v_mul_f32_e32 v44, v45, v44
	v_mul_f32_e32 v35, v40, v35
	v_mul_f32_e32 v35, v36, v35
	v_mul_f32_e32 v36, 0xbfb8aa3b, v41
	v_exp_f32_e32 v36, v36
	v_cvt_pk_bf16_f32 v43, v43, v44
	v_cvt_pk_bf16_f32 v51, v51, v52
	ds_write2_b64 v60, v[62:63], v[50:51] offset1:4
	v_add_f32_e32 v36, 1.0, v36
	v_rcp_f32_e32 v36, v36
	s_nop 0
	v_mul_f32_e32 v36, v41, v36
	v_mul_f32_e32 v36, v37, v36
	v_cvt_pk_bf16_f32 v35, v35, v36
	ds_write2_b64 v0, v[42:43], v[34:35] offset0:32 offset1:36
	v_mul_f32_e32 v0, 0xbfb8aa3b, v30
	v_exp_f32_e32 v0, v0
	s_nop 0
	v_add_f32_e32 v0, 1.0, v0
	v_rcp_f32_e32 v0, v0
	s_nop 0
	v_mul_f32_e32 v0, v30, v0
	v_mul_f32_e32 v0, v26, v0
	v_mul_f32_e32 v26, 0xbfb8aa3b, v31
	v_exp_f32_e32 v26, v26
	s_nop 0
	v_add_f32_e32 v26, 1.0, v26
	v_rcp_f32_e32 v26, v26
	s_nop 0
	v_mul_f32_e32 v26, v31, v26
	v_mul_f32_e32 v26, v27, v26
	v_cvt_pk_bf16_f32 v26, v0, v26
	v_mul_f32_e32 v0, 0xbfb8aa3b, v22
	v_exp_f32_e32 v0, v0
	v_mul_f32_e32 v27, 0xbfb8aa3b, v32
	v_exp_f32_e32 v27, v27
	v_add_f32_e32 v0, 1.0, v0
	v_rcp_f32_e32 v0, v0
	v_add_f32_e32 v27, 1.0, v27
	v_rcp_f32_e32 v27, v27
	v_mul_f32_e32 v0, v22, v0
	v_mul_f32_e32 v0, v18, v0
	v_mul_f32_e32 v18, 0xbfb8aa3b, v23
	v_exp_f32_e32 v18, v18
	v_mul_f32_e32 v27, v32, v27
	v_mul_f32_e32 v27, v28, v27
	v_mul_f32_e32 v28, 0xbfb8aa3b, v33
	v_add_f32_e32 v18, 1.0, v18
	v_rcp_f32_e32 v18, v18
	v_exp_f32_e32 v28, v28
	v_mul_f32_e32 v18, v23, v18
	v_mul_f32_e32 v18, v19, v18
	v_mul_f32_e32 v19, 0xbfb8aa3b, v24
	v_exp_f32_e32 v19, v19
	v_add_f32_e32 v28, 1.0, v28
	v_rcp_f32_e32 v28, v28
	v_cvt_pk_bf16_f32 v18, v0, v18
	v_add_f32_e32 v19, 1.0, v19
	v_rcp_f32_e32 v19, v19
	v_mul_f32_e32 v28, v33, v28
	v_add_u32_e32 v0, 0x1000, v60
	v_mul_f32_e32 v28, v29, v28
	v_mul_f32_e32 v19, v24, v19
	v_mul_f32_e32 v19, v20, v19
	v_mul_f32_e32 v20, 0xbfb8aa3b, v25
	v_exp_f32_e32 v20, v20
	v_cvt_pk_bf16_f32 v27, v27, v28
	s_nop 0
	v_add_f32_e32 v20, 1.0, v20
	v_rcp_f32_e32 v20, v20
	s_nop 0
	v_mul_f32_e32 v20, v25, v20
	v_mul_f32_e32 v20, v21, v20
	v_cvt_pk_bf16_f32 v19, v19, v20
	ds_write2_b64 v0, v[26:27], v[18:19] offset0:64 offset1:68
	v_mul_f32_e32 v0, 0xbfb8aa3b, v10
	v_exp_f32_e32 v0, v0
	s_nop 0
	v_add_f32_e32 v0, 1.0, v0
	v_rcp_f32_e32 v0, v0
	s_nop 0
	v_mul_f32_e32 v0, v10, v0
	v_mul_f32_e32 v10, 0xbfb8aa3b, v11
	v_exp_f32_e32 v10, v10
	v_mul_f32_e32 v0, v14, v0
	v_add_f32_e32 v10, 1.0, v10
	v_rcp_f32_e32 v10, v10
	s_nop 0
	v_mul_f32_e32 v10, v11, v10
	v_mul_f32_e32 v10, v15, v10
	v_cvt_pk_bf16_f32 v10, v0, v10
	v_mul_f32_e32 v0, 0xbfb8aa3b, v2
	v_exp_f32_e32 v0, v0
	v_mul_f32_e32 v11, 0xbfb8aa3b, v12
	v_exp_f32_e32 v11, v11
	v_add_f32_e32 v0, 1.0, v0
	v_rcp_f32_e32 v0, v0
	v_add_f32_e32 v11, 1.0, v11
	v_rcp_f32_e32 v11, v11
	v_mul_f32_e32 v0, v2, v0
	v_mul_f32_e32 v2, 0xbfb8aa3b, v3
	v_exp_f32_e32 v2, v2
	v_mul_f32_e32 v11, v12, v11
	v_mul_f32_e32 v12, 0xbfb8aa3b, v13
	v_exp_f32_e32 v12, v12
	v_add_f32_e32 v2, 1.0, v2
	v_rcp_f32_e32 v2, v2
	v_mul_f32_e32 v11, v16, v11
	v_add_f32_e32 v12, 1.0, v12
	v_rcp_f32_e32 v12, v12
	v_mul_f32_e32 v2, v3, v2
	v_mul_f32_e32 v3, 0xbfb8aa3b, v4
	v_exp_f32_e32 v3, v3
	v_mul_f32_e32 v12, v13, v12
	v_mul_f32_e32 v0, v6, v0
	v_mul_f32_e32 v2, v7, v2
	v_add_f32_e32 v3, 1.0, v3
	v_rcp_f32_e32 v3, v3
	v_mul_f32_e32 v12, v17, v12
	v_cvt_pk_bf16_f32 v11, v11, v12
	v_cvt_pk_bf16_f32 v2, v0, v2
	v_mul_f32_e32 v3, v4, v3
	v_mul_f32_e32 v4, 0xbfb8aa3b, v5
	v_exp_f32_e32 v4, v4
	v_mul_f32_e32 v3, v8, v3
	v_add_u32_e32 v0, 0x1800, v60
	v_add_f32_e32 v4, 1.0, v4
	v_rcp_f32_e32 v4, v4
	s_nop 0
	v_mul_f32_e32 v4, v5, v4
	v_mul_f32_e32 v4, v9, v4
	v_cvt_pk_bf16_f32 v3, v3, v4
	ds_write2_b64 v0, v[10:11], v[2:3] offset0:96 offset1:100
	v_mov_b32_e32 v11, v163
	s_waitcnt lgkmcnt(0)
	s_barrier
	v_lshl_add_u64 v[2:3], v[58:59], 1, s[78:79]
	v_lshlrev_b32_e32 v0, 4, v11
	v_and_b32_e32 v0, 0x70, v0
	v_ashrrev_i32_e32 v8, 3, v11
	v_lshl_add_u64 v[6:7], v[2:3], 0, v[0:1]
	v_mad_u64_u32 v[2:3], s[2:3], v8, s4, v[0:1]
	ds_read_b128 v[2:5], v2
	v_lshlrev_b32_e32 v10, 7, v135
	v_add_u32_e32 v8, v8, v10
	v_mad_i64_i32 v[8:9], s[2:3], v8, s38, v[6:7]
	s_waitcnt lgkmcnt(0)
	global_store_dwordx4 v[8:9], v[2:5], off nt
	s_nop 1
	v_add_u32_e32 v2, 0x100, v11
	v_ashrrev_i32_e32 v8, 3, v2
	v_mad_u64_u32 v[2:3], s[2:3], v8, s4, v[0:1]
	ds_read_b128 v[2:5], v2
	v_add_u32_e32 v8, v8, v10
	v_mad_i64_i32 v[8:9], s[2:3], v8, s38, v[6:7]
	s_waitcnt lgkmcnt(0)
	global_store_dwordx4 v[8:9], v[2:5], off nt
	s_nop 1
	v_add_u32_e32 v2, 0x200, v11
	v_ashrrev_i32_e32 v8, 3, v2
	v_mad_u64_u32 v[2:3], s[2:3], v8, s4, v[0:1]
	ds_read_b128 v[2:5], v2
	v_add_u32_e32 v8, v8, v10
	v_mad_i64_i32 v[8:9], s[2:3], v8, s38, v[6:7]
	s_waitcnt lgkmcnt(0)
	global_store_dwordx4 v[8:9], v[2:5], off nt
	s_nop 1
	v_add_u32_e32 v2, 0x300, v11
	v_ashrrev_i32_e32 v8, 3, v2
	v_mad_u64_u32 v[2:3], s[2:3], v8, s4, v[0:1]
	ds_read_b128 v[2:5], v2
	v_add_u32_e32 v0, v8, v10
	v_mad_i64_i32 v[6:7], s[2:3], v0, s38, v[6:7]
	s_movk_i32 s2, 0x15ff
	s_waitcnt lgkmcnt(0)
	global_store_dwordx4 v[6:7], v[2:5], off nt
	s_barrier
	global_load_dword v0, v[164:165], off
	s_waitcnt vmcnt(0)
	v_add_u32_e32 v134, v0, v134
	v_cmp_lt_i32_e32 vcc, s2, v134
	s_or_b64 s[0:1], vcc, s[0:1]
	s_andn2_b64 exec, exec, s[0:1]
	s_cbranch_execz .LBB0_67
.LBB0_59:
	s_movk_i32 s2, 0x13ff
	v_and_b32_e32 v0, 7, v134
	v_cmp_lt_i32_e32 vcc, s2, v134
	s_and_saveexec_b64 s[2:3], vcc
	s_xor_b64 s[2:3], exec, s[2:3]
	v_add_u32_e32 v2, 0xffffec00, v134
	v_bfe_u32 v3, v134, 3, 4
	v_lshl_or_b32 v135, v0, 4, v3
	v_lshrrev_b32_e32 v0, 7, v2
	v_add_u32_e32 v136, 40, v0
	s_andn2_saveexec_b64 s[2:3], s[2:3]
	v_lshrrev_b32_e32 v3, 6, v134
	v_bfe_u32 v2, v134, 3, 3
	v_lshlrev_b32_e32 v0, 4, v0
	v_and_b32_e32 v4, 8, v3
	v_or3_b32 v135, v0, v4, v2
	v_ashrrev_i32_e32 v0, 7, v134
	v_bfi_b32 v136, -8, v0, v3
	s_or_b64 exec, exec, s[2:3]
	v_mov_b64_e32 v[2:3], s[80:81]
	s_mov_b32 s4, 0x44000
	v_mad_u64_u32 v[4:5], s[2:3], v135, s4, v[2:3]
	v_mov_b64_e32 v[2:3], s[56:57]
	v_mad_i64_i32 v[6:7], s[2:3], v136, s4, v[2:3]
	v_mov_b32_e32 v2, v163
	s_mov_b32 s4, 0x22000
	v_ashrrev_i32_e32 v3, 3, v2
	v_lshlrev_b32_e32 v0, 4, v2
	v_mad_i64_i32 v[4:5], s[2:3], v3, s43, v[4:5]
	v_and_b32_e32 v0, 0x70, v0
	v_lshl_add_u64 v[130:131], v[4:5], 0, v[0:1]
	v_mad_i64_i32 v[4:5], s[2:3], v3, s43, v[6:7]
	v_lshl_add_u64 v[132:133], v[4:5], 0, v[0:1]
	v_and_b32_e32 v110, 7, v163
	v_bfe_u32 v111, v163, 4, 3
	v_xor_b32_e32 v111, v111, v110
	v_sub_u32_e32 v111, v111, v110
	v_lshlrev_b32_e32 v111, 4, v111
	v_lshrrev_b32_e32 v112, 6, v163
	v_lshlrev_b32_e32 v112, 10, v112
	v_readfirstlane_b32 s2, v130
	v_readfirstlane_b32 s3, v131
	v_readfirstlane_b32 s4, v132
	v_readfirstlane_b32 s5, v133
	v_readfirstlane_b32 s6, v112
	s_nop 3
	v_subrev_u32_e32 v98, s2, v130
	v_subrev_u32_e32 v102, s4, v132
	v_add_u32_e32 v98, v98, v111
	v_add_u32_e32 v102, v102, v111
	v_add_u32_e32 v99, 0x11000, v98
	v_add_u32_e32 v103, 0x11000, v102
	v_add_u32_e32 v100, 0x22000, v98
	v_add_u32_e32 v104, 0x22000, v102
	v_add_u32_e32 v101, 0x33000, v98
	v_add_u32_e32 v105, 0x33000, v102
	v_lshlrev_b32_e32 v110, 3, v163
	v_lshlrev_b32_e32 v111, 7, v163
	v_and_b32_e32 v112, 0x2000, v111
	v_and_b32_e32 v111, 0x780, v111
	v_and_b32_e32 v107, 64, v110
	v_xor_b32_e32 v110, v110, v163
	v_and_b32_e32 v110, 48, v110
	v_or3_b32 v110, v111, v107, v110
	v_lshlrev_b32_e32 v111, 6, v163
	v_and_b32_e32 v111, 0xffffe000, v111
	v_or_b32_e32 v108, v110, v112
	v_or_b32_e32 v106, v110, v111
	v_xor_b32_e32 v107, 64, v106
	v_xor_b32_e32 v109, 64, v108
	s_mov_b32 m0, s6
	s_nop 0
	global_load_lds_dwordx4 v98, s[2:3]
	s_add_u32 m0, s6, 0x1000
	s_nop 0
	global_load_lds_dwordx4 v99, s[2:3]
	s_add_u32 m0, s6, 0x2000
	s_nop 0
	global_load_lds_dwordx4 v100, s[2:3]
	s_add_u32 m0, s6, 0x3000
	s_nop 0
	global_load_lds_dwordx4 v101, s[2:3]
	s_add_u32 m0, s6, 0x4000
	s_nop 0
	global_load_lds_dwordx4 v102, s[4:5]
	s_add_u32 m0, s6, 0x5000
	s_nop 0
	global_load_lds_dwordx4 v103, s[4:5]
	s_add_u32 m0, s6, 0x6000
	s_nop 0
	global_load_lds_dwordx4 v104, s[4:5]
	s_add_u32 m0, s6, 0x7000
	s_nop 0
	global_load_lds_dwordx4 v105, s[4:5]
	s_waitcnt vmcnt(0)
	s_add_u32 s2, s2, 0x80
	s_addc_u32 s3, s3, 0
	s_add_u32 s4, s4, 0x80
	s_addc_u32 s5, s5, 0
	s_barrier
	s_add_u32 m0, s6, 0x8000
	ds_read_b128 v[142:145], v106
	ds_read_b128 v[158:161], v108 offset:16384
	s_nop 0
	global_load_lds_dwordx4 v98, s[2:3]
	s_add_u32 m0, s6, 0x9000
	ds_read_b128 v[182:185], v108 offset:18432
	ds_read_b128 v[186:189], v108 offset:20480
	s_nop 0
	global_load_lds_dwordx4 v99, s[2:3]
	s_add_u32 m0, s6, 0xa000
	ds_read_b128 v[206:209], v108 offset:22528
	ds_read_b128 v[146:149], v106 offset:2048
	s_nop 0
	global_load_lds_dwordx4 v100, s[2:3]
	s_add_u32 m0, s6, 0xb000
	ds_read_b128 v[150:153], v106 offset:4096
	ds_read_b128 v[154:157], v106 offset:6144
	s_nop 0
	global_load_lds_dwordx4 v101, s[2:3]
	s_add_u32 m0, s6, 0xc000
	s_nop 0
	global_load_lds_dwordx4 v102, s[4:5]
	s_add_u32 m0, s6, 0xd000
	s_nop 0
	global_load_lds_dwordx4 v103, s[4:5]
	s_add_u32 m0, s6, 0xe000
	s_nop 0
	global_load_lds_dwordx4 v104, s[4:5]
	s_add_u32 m0, s6, 0xf000
	s_nop 0
	global_load_lds_dwordx4 v105, s[4:5]
	s_add_u32 s2, s2, 0x80
	s_addc_u32 s3, s3, 0
	s_add_u32 s4, s4, 0x80
	s_addc_u32 s5, s5, 0
	s_waitcnt lgkmcnt(0)
	v_mfma_f32_16x16x32_bf16 v[90:93], v[158:161], v[142:145], 0
	ds_read_b128 v[58:61], v107
	ds_read_b128 v[74:77], v109 offset:16384
	v_mfma_f32_16x16x32_bf16 v[54:57], v[182:185], v[142:145], 0
	v_mfma_f32_16x16x32_bf16 v[86:89], v[186:189], v[142:145], 0
	ds_read_b128 v[78:81], v109 offset:18432
	ds_read_b128 v[82:85], v109 offset:20480
	v_mfma_f32_16x16x32_bf16 v[50:53], v[206:209], v[142:145], 0
	v_mfma_f32_16x16x32_bf16 v[46:49], v[158:161], v[146:149], 0
	ds_read_b128 v[94:97], v109 offset:22528
	ds_read_b128 v[62:65], v107 offset:2048
	v_mfma_f32_16x16x32_bf16 v[38:41], v[182:185], v[146:149], 0
	v_mfma_f32_16x16x32_bf16 v[42:45], v[186:189], v[146:149], 0
	ds_read_b128 v[66:69], v107 offset:4096
	ds_read_b128 v[70:73], v107 offset:6144
	v_mfma_f32_16x16x32_bf16 v[34:37], v[206:209], v[146:149], 0
	v_mfma_f32_16x16x32_bf16 v[30:33], v[158:161], v[150:153], 0
	v_mfma_f32_16x16x32_bf16 v[22:25], v[182:185], v[150:153], 0
	v_mfma_f32_16x16x32_bf16 v[26:29], v[186:189], v[150:153], 0
	v_mfma_f32_16x16x32_bf16 v[18:21], v[206:209], v[150:153], 0
	v_mfma_f32_16x16x32_bf16 v[10:13], v[158:161], v[154:157], 0
	v_mfma_f32_16x16x32_bf16 v[2:5], v[182:185], v[154:157], 0
	v_mfma_f32_16x16x32_bf16 v[14:17], v[186:189], v[154:157], 0
	v_mfma_f32_16x16x32_bf16 v[6:9], v[206:209], v[154:157], 0
	s_waitcnt vmcnt(0) lgkmcnt(0)
	s_barrier
	s_movk_i32 s7, 7

.LBB0_82:
	v_lshrrev_b32_e32 v2, 6, v134
	v_lshlrev_b32_e32 v3, 4, v134
	v_bfe_u32 v0, v134, 3, 3
	v_and_b32_e32 v3, 0x70, v3
	v_and_b32_e32 v4, 8, v2
	v_or3_b32 v135, v3, v4, v0
	v_ashrrev_i32_e32 v0, 7, v134
	v_bfi_b32 v136, -8, v0, v2
	v_mul_u32_u24_e32 v0, 0x22000, v135
	v_mov_b64_e32 v[2:3], s[54:55]
	s_mov_b32 s2, 0x44000
	v_lshlrev_b32_e32 v0, 1, v0
	v_mad_i64_i32 v[6:7], s[2:3], v136, s2, v[2:3]
	v_mov_b32_e32 v2, v163
	v_lshl_add_u64 v[4:5], s[80:81], 0, v[0:1]
	s_mov_b32 s4, 0x22000
	v_ashrrev_i32_e32 v3, 3, v2
	v_lshlrev_b32_e32 v0, 4, v2
	v_mad_i64_i32 v[4:5], s[2:3], v3, s43, v[4:5]
	v_and_b32_e32 v0, 0x70, v0
	v_lshl_add_u64 v[130:131], v[4:5], 0, v[0:1]
	v_mad_i64_i32 v[4:5], s[2:3], v3, s43, v[6:7]
	v_lshl_add_u64 v[132:133], v[4:5], 0, v[0:1]
	v_and_b32_e32 v110, 7, v163
	v_bfe_u32 v111, v163, 4, 3
	v_xor_b32_e32 v111, v111, v110
	v_sub_u32_e32 v111, v111, v110
	v_lshlrev_b32_e32 v111, 4, v111
	v_lshrrev_b32_e32 v112, 6, v163
	v_lshlrev_b32_e32 v112, 10, v112
	v_readfirstlane_b32 s2, v130
	v_readfirstlane_b32 s3, v131
	v_readfirstlane_b32 s4, v132
	v_readfirstlane_b32 s5, v133
	v_readfirstlane_b32 s6, v112
	s_nop 3
	v_subrev_u32_e32 v98, s2, v130
	v_subrev_u32_e32 v102, s4, v132
	v_add_u32_e32 v98, v98, v111
	v_add_u32_e32 v102, v102, v111
	v_add_u32_e32 v99, 0x11000, v98
	v_add_u32_e32 v103, 0x11000, v102
	v_add_u32_e32 v100, 0x22000, v98
	v_add_u32_e32 v104, 0x22000, v102
	v_add_u32_e32 v101, 0x33000, v98
	v_add_u32_e32 v105, 0x33000, v102
	v_lshlrev_b32_e32 v110, 3, v163
	v_lshlrev_b32_e32 v111, 7, v163
	v_and_b32_e32 v112, 0x2000, v111
	v_and_b32_e32 v111, 0x780, v111
	v_and_b32_e32 v107, 64, v110
	v_xor_b32_e32 v110, v110, v163
	v_and_b32_e32 v110, 48, v110
	v_or3_b32 v110, v111, v107, v110
	v_lshlrev_b32_e32 v111, 6, v163
	v_and_b32_e32 v111, 0xffffe000, v111
	v_or_b32_e32 v108, v110, v112
	v_or_b32_e32 v106, v110, v111
	v_xor_b32_e32 v107, 64, v106
	v_xor_b32_e32 v109, 64, v108
	s_mov_b32 m0, s6
	s_nop 0
	global_load_lds_dwordx4 v98, s[2:3]
	s_add_u32 m0, s6, 0x1000
	s_nop 0
	global_load_lds_dwordx4 v99, s[2:3]
	s_add_u32 m0, s6, 0x2000
	s_nop 0
	global_load_lds_dwordx4 v100, s[2:3]
	s_add_u32 m0, s6, 0x3000
	s_nop 0
	global_load_lds_dwordx4 v101, s[2:3]
	s_add_u32 m0, s6, 0x4000
	s_nop 0
	global_load_lds_dwordx4 v102, s[4:5]
	s_add_u32 m0, s6, 0x5000
	s_nop 0
	global_load_lds_dwordx4 v103, s[4:5]
	s_add_u32 m0, s6, 0x6000
	s_nop 0
	global_load_lds_dwordx4 v104, s[4:5]
	s_add_u32 m0, s6, 0x7000
	s_nop 0
	global_load_lds_dwordx4 v105, s[4:5]
	s_waitcnt vmcnt(0)
	s_add_u32 s2, s2, 0x80
	s_addc_u32 s3, s3, 0
	s_add_u32 s4, s4, 0x80
	s_addc_u32 s5, s5, 0
	s_barrier
	s_add_u32 m0, s6, 0x8000
	ds_read_b128 v[142:145], v106
	ds_read_b128 v[158:161], v108 offset:16384
	s_nop 0
	global_load_lds_dwordx4 v98, s[2:3]
	s_add_u32 m0, s6, 0x9000
	ds_read_b128 v[182:185], v108 offset:18432
	ds_read_b128 v[186:189], v108 offset:20480
	s_nop 0
	global_load_lds_dwordx4 v99, s[2:3]
	s_add_u32 m0, s6, 0xa000
	ds_read_b128 v[206:209], v108 offset:22528
	ds_read_b128 v[146:149], v106 offset:2048
	s_nop 0
	global_load_lds_dwordx4 v100, s[2:3]
	s_add_u32 m0, s6, 0xb000
	ds_read_b128 v[150:153], v106 offset:4096
	ds_read_b128 v[154:157], v106 offset:6144
	s_nop 0
	global_load_lds_dwordx4 v101, s[2:3]
	s_add_u32 m0, s6, 0xc000
	s_nop 0
	global_load_lds_dwordx4 v102, s[4:5]
	s_add_u32 m0, s6, 0xd000
	s_nop 0
	global_load_lds_dwordx4 v103, s[4:5]
	s_add_u32 m0, s6, 0xe000
	s_nop 0
	global_load_lds_dwordx4 v104, s[4:5]
	s_add_u32 m0, s6, 0xf000
	s_nop 0
	global_load_lds_dwordx4 v105, s[4:5]
	s_add_u32 s2, s2, 0x80
	s_addc_u32 s3, s3, 0
	s_add_u32 s4, s4, 0x80
	s_addc_u32 s5, s5, 0
	s_waitcnt lgkmcnt(0)
	v_mfma_f32_16x16x32_bf16 v[94:97], v[158:161], v[142:145], 0
	ds_read_b128 v[34:37], v107
	ds_read_b128 v[54:57], v109 offset:16384
	v_mfma_f32_16x16x32_bf16 v[90:93], v[182:185], v[142:145], 0
	v_mfma_f32_16x16x32_bf16 v[86:89], v[186:189], v[142:145], 0
	ds_read_b128 v[62:65], v109 offset:18432
	ds_read_b128 v[66:69], v109 offset:20480
	v_mfma_f32_16x16x32_bf16 v[82:85], v[206:209], v[142:145], 0
	v_mfma_f32_16x16x32_bf16 v[74:77], v[158:161], v[146:149], 0
	ds_read_b128 v[78:81], v109 offset:22528
	ds_read_b128 v[38:41], v107 offset:2048
	v_mfma_f32_16x16x32_bf16 v[70:73], v[182:185], v[146:149], 0
	v_mfma_f32_16x16x32_bf16 v[58:61], v[186:189], v[146:149], 0
	ds_read_b128 v[46:49], v107 offset:4096
	ds_read_b128 v[50:53], v107 offset:6144
	v_mfma_f32_16x16x32_bf16 v[42:45], v[206:209], v[146:149], 0
	v_mfma_f32_16x16x32_bf16 v[30:33], v[158:161], v[150:153], 0
	v_mfma_f32_16x16x32_bf16 v[26:29], v[182:185], v[150:153], 0
	v_mfma_f32_16x16x32_bf16 v[22:25], v[186:189], v[150:153], 0
	v_mfma_f32_16x16x32_bf16 v[18:21], v[206:209], v[150:153], 0
	v_mfma_f32_16x16x32_bf16 v[14:17], v[158:161], v[154:157], 0
	v_mfma_f32_16x16x32_bf16 v[10:13], v[182:185], v[154:157], 0
	v_mfma_f32_16x16x32_bf16 v[6:9], v[186:189], v[154:157], 0
	v_mfma_f32_16x16x32_bf16 v[2:5], v[206:209], v[154:157], 0
	s_waitcnt vmcnt(0) lgkmcnt(0)
	s_barrier
	s_movk_i32 s7, 7

.LBB0_273:
	v_mov_b32_e32 v0, v163
	s_bfe_u32 s7, s3, 0x30002
	v_mov_b64_e32 v[4:5], s[78:79]
	v_ashrrev_i32_e32 v2, 4, v0
	v_lshl_add_u32 v2, s7, 6, v2
	v_ashrrev_i32_e32 v3, 31, v2
	v_lshlrev_b64 v[2:3], 5, v[2:3]
	v_or_b32_e32 v2, s0, v2
	s_ashr_i32 s4, s3, 6
	s_bfe_u32 s5, s3, 0x10005
	v_mad_u64_u32 v[4:5], s[8:9], v2, s93, v[4:5]
	s_cmp_lt_u32 s3, 64
	s_movk_i32 s8, 0x1400
	s_mul_i32 s9, s4, 0x108000
	s_cselect_b32 s40, s8, 0x1500
	s_mul_hi_i32 s8, s4, 0x108000
	s_add_u32 s9, s76, s9
	s_addc_u32 s8, s77, s8
	s_mul_i32 s10, s5, 0x84000
	v_mad_i32_i24 v5, v3, s93, v5
	s_add_u32 s9, s9, s10
	v_lshl_add_u64 v[2:3], v[4:5], 0, s[40:41]
	v_lshlrev_b32_e32 v4, 4, v0
	s_addc_u32 s10, s8, 0
	v_and_b32_e32 v0, 0x80, v4
	s_add_u32 s8, s9, s2
	v_lshl_add_u64 v[2:3], v[2:3], 0, v[0:1]
	v_and_b32_e32 v0, 0x70, v4
	s_addc_u32 s9, s10, 0
	v_mov_b32_e32 v30, v163
	v_lshl_add_u64 v[130:131], v[2:3], 0, v[0:1]
	v_mov_b64_e32 v[2:3], s[8:9]
	v_ashrrev_i32_e32 v31, 3, v30
	s_movk_i32 s8, 0x1080
	v_lshlrev_b32_e32 v0, 4, v30
	v_mad_i64_i32 v[2:3], s[8:9], v31, s8, v[2:3]
	v_and_b32_e32 v0, 0x70, v0
	s_mov_b32 s15, 0x660000
	v_lshl_add_u64 v[132:133], v[2:3], 0, v[0:1]
	v_and_b32_e32 v110, 7, v163
	v_bfe_u32 v111, v163, 4, 3
	v_xor_b32_e32 v111, v111, v110
	v_sub_u32_e32 v111, v111, v110
	v_lshlrev_b32_e32 v111, 4, v111
	v_lshrrev_b32_e32 v112, 6, v163
	v_lshlrev_b32_e32 v112, 10, v112
	v_readfirstlane_b32 s8, v130
	v_readfirstlane_b32 s9, v131
	v_readfirstlane_b32 s10, v132
	v_readfirstlane_b32 s11, v133
	v_readfirstlane_b32 s12, v112
	s_nop 3
	v_subrev_u32_e32 v98, s8, v130
	v_subrev_u32_e32 v102, s10, v132
	v_add_u32_e32 v98, v98, v111
	v_add_u32_e32 v102, v102, v111
	v_add_u32_e32 v99, 0x660000, v98
	v_add_u32_e32 v103, 0x21000, v102
	v_add_u32_e32 v100, 0xcc0000, v98
	v_add_u32_e32 v104, 0x42000, v102
	v_add_u32_e32 v101, 0x1320000, v98
	v_add_u32_e32 v105, 0x63000, v102
	v_lshlrev_b32_e32 v110, 3, v163
	v_lshlrev_b32_e32 v111, 7, v163
	v_and_b32_e32 v112, 0x2000, v111
	v_and_b32_e32 v111, 0x780, v111
	v_and_b32_e32 v107, 64, v110
	v_xor_b32_e32 v110, v110, v163
	v_and_b32_e32 v110, 48, v110
	v_or3_b32 v110, v111, v107, v110
	v_lshlrev_b32_e32 v111, 6, v163
	v_and_b32_e32 v111, 0xffffe000, v111
	v_or_b32_e32 v108, v110, v112
	v_or_b32_e32 v106, v110, v111
	v_xor_b32_e32 v107, 64, v106
	v_xor_b32_e32 v109, 64, v108
	s_mov_b32 m0, s12
	s_nop 0
	global_load_lds_dwordx4 v98, s[8:9]
	s_add_u32 m0, s12, 0x1000
	s_nop 0
	global_load_lds_dwordx4 v99, s[8:9]
	s_add_u32 m0, s12, 0x2000
	s_nop 0
	global_load_lds_dwordx4 v100, s[8:9]
	s_add_u32 m0, s12, 0x3000
	s_nop 0
	global_load_lds_dwordx4 v101, s[8:9]
	s_add_u32 m0, s12, 0x4000
	s_nop 0
	global_load_lds_dwordx4 v102, s[10:11]
	s_add_u32 m0, s12, 0x5000
	s_nop 0
	global_load_lds_dwordx4 v103, s[10:11]
	s_add_u32 m0, s12, 0x6000
	s_nop 0
	global_load_lds_dwordx4 v104, s[10:11]
	s_add_u32 m0, s12, 0x7000
	s_nop 0
	global_load_lds_dwordx4 v105, s[10:11]
	s_waitcnt vmcnt(0)
	s_add_u32 s8, s8, 0x3300
	s_addc_u32 s9, s9, 0
	s_add_u32 s10, s10, 0x80
	s_addc_u32 s11, s11, 0
	s_barrier
	s_add_u32 m0, s12, 0x8000
	ds_read_b128 v[138:141], v106
	ds_read_b128 v[154:157], v108 offset:16384
	s_nop 0
	global_load_lds_dwordx4 v98, s[8:9]
	s_add_u32 m0, s12, 0x9000
	ds_read_b128 v[158:161], v108 offset:18432
	ds_read_b128 v[182:185], v108 offset:20480
	s_nop 0
	global_load_lds_dwordx4 v99, s[8:9]
	s_add_u32 m0, s12, 0xa000
	ds_read_b128 v[186:189], v108 offset:22528
	ds_read_b128 v[142:145], v106 offset:2048
	s_nop 0
	global_load_lds_dwordx4 v100, s[8:9]
	s_add_u32 m0, s12, 0xb000
	ds_read_b128 v[146:149], v106 offset:4096
	ds_read_b128 v[150:153], v106 offset:6144
	s_nop 0
	global_load_lds_dwordx4 v101, s[8:9]
	s_add_u32 m0, s12, 0xc000
	s_nop 0
	global_load_lds_dwordx4 v102, s[10:11]
	s_add_u32 m0, s12, 0xd000
	s_nop 0
	global_load_lds_dwordx4 v103, s[10:11]
	s_add_u32 m0, s12, 0xe000
	s_nop 0
	global_load_lds_dwordx4 v104, s[10:11]
	s_add_u32 m0, s12, 0xf000
	s_nop 0
	global_load_lds_dwordx4 v105, s[10:11]
	s_add_u32 s8, s8, 0x3300
	s_addc_u32 s9, s9, 0
	s_add_u32 s10, s10, 0x80
	s_addc_u32 s11, s11, 0
	s_waitcnt lgkmcnt(0)
	v_mfma_f32_16x16x32_bf16 v[94:97], v[154:157], v[138:141], 0
	ds_read_b128 v[2:5], v107
	ds_read_b128 v[18:21], v109 offset:16384
	v_mfma_f32_16x16x32_bf16 v[90:93], v[158:161], v[138:141], 0
	v_mfma_f32_16x16x32_bf16 v[86:89], v[182:185], v[138:141], 0
	ds_read_b128 v[22:25], v109 offset:18432
	ds_read_b128 v[26:29], v109 offset:20480
	v_mfma_f32_16x16x32_bf16 v[82:85], v[186:189], v[138:141], 0
	v_mfma_f32_16x16x32_bf16 v[78:81], v[154:157], v[142:145], 0
	ds_read_b128 v[54:57], v109 offset:22528
	ds_read_b128 v[6:9], v107 offset:2048
	v_mfma_f32_16x16x32_bf16 v[70:73], v[158:161], v[142:145], 0
	v_mfma_f32_16x16x32_bf16 v[66:69], v[182:185], v[142:145], 0
	ds_read_b128 v[10:13], v107 offset:4096
	ds_read_b128 v[14:17], v107 offset:6144
	v_mfma_f32_16x16x32_bf16 v[62:65], v[186:189], v[142:145], 0
	v_mfma_f32_16x16x32_bf16 v[58:61], v[154:157], v[146:149], 0
	v_mfma_f32_16x16x32_bf16 v[50:53], v[158:161], v[146:149], 0
	v_mfma_f32_16x16x32_bf16 v[46:49], v[182:185], v[146:149], 0
	v_mfma_f32_16x16x32_bf16 v[42:45], v[186:189], v[146:149], 0
	v_mfma_f32_16x16x32_bf16 v[38:41], v[154:157], v[150:153], 0
	v_mfma_f32_16x16x32_bf16 v[34:37], v[158:161], v[150:153], 0
	v_mfma_f32_16x16x32_bf16 v[30:33], v[182:185], v[150:153], 0
	v_mfma_f32_16x16x32_bf16 v[74:77], v[186:189], v[150:153], 0
	s_waitcnt vmcnt(0) lgkmcnt(0)
	s_barrier
	s_movk_i32 s13, 3

.LBB0_398:
	v_mov_b64_e32 v[2:3], s[80:81]
	s_mov_b32 s4, 0x44000
	v_mad_u64_u32 v[4:5], s[0:1], v136, s4, v[2:3]
	v_mov_b64_e32 v[2:3], s[46:47]
	v_mad_i64_i32 v[6:7], s[0:1], v135, s4, v[2:3]
	v_mov_b32_e32 v2, v163
	s_mov_b32 s4, 0x22000
	v_ashrrev_i32_e32 v3, 3, v2
	v_lshlrev_b32_e32 v0, 4, v2
	v_mad_i64_i32 v[4:5], s[0:1], v3, s43, v[4:5]
	v_and_b32_e32 v0, 0x70, v0
	v_lshl_add_u64 v[130:131], v[4:5], 0, v[0:1]
	v_mad_i64_i32 v[4:5], s[0:1], v3, s43, v[6:7]
	v_lshl_add_u64 v[132:133], v[4:5], 0, v[0:1]
	v_and_b32_e32 v110, 7, v163
	v_bfe_u32 v111, v163, 4, 3
	v_xor_b32_e32 v111, v111, v110
	v_sub_u32_e32 v111, v111, v110
	v_lshlrev_b32_e32 v111, 4, v111
	v_lshrrev_b32_e32 v112, 6, v163
	v_lshlrev_b32_e32 v112, 10, v112
	v_readfirstlane_b32 s0, v130
	v_readfirstlane_b32 s1, v131
	v_readfirstlane_b32 s4, v132
	v_readfirstlane_b32 s5, v133
	v_readfirstlane_b32 s8, v112
	s_nop 3
	v_subrev_u32_e32 v98, s0, v130
	v_subrev_u32_e32 v102, s4, v132
	v_add_u32_e32 v98, v98, v111
	v_add_u32_e32 v102, v102, v111
	v_add_u32_e32 v99, 0x11000, v98
	v_add_u32_e32 v103, 0x11000, v102
	v_add_u32_e32 v100, 0x22000, v98
	v_add_u32_e32 v104, 0x22000, v102
	v_add_u32_e32 v101, 0x33000, v98
	v_add_u32_e32 v105, 0x33000, v102
	v_lshlrev_b32_e32 v110, 3, v163
	v_lshlrev_b32_e32 v111, 7, v163
	v_and_b32_e32 v112, 0x2000, v111
	v_and_b32_e32 v111, 0x780, v111
	v_and_b32_e32 v107, 64, v110
	v_xor_b32_e32 v110, v110, v163
	v_and_b32_e32 v110, 48, v110
	v_or3_b32 v110, v111, v107, v110
	v_lshlrev_b32_e32 v111, 6, v163
	v_and_b32_e32 v111, 0xffffe000, v111
	v_or_b32_e32 v108, v110, v112
	v_or_b32_e32 v106, v110, v111
	v_xor_b32_e32 v107, 64, v106
	v_xor_b32_e32 v109, 64, v108
	s_mov_b32 m0, s8
	s_nop 0
	global_load_lds_dwordx4 v98, s[0:1]
	s_add_u32 m0, s8, 0x1000
	s_nop 0
	global_load_lds_dwordx4 v99, s[0:1]
	s_add_u32 m0, s8, 0x2000
	s_nop 0
	global_load_lds_dwordx4 v100, s[0:1]
	s_add_u32 m0, s8, 0x3000
	s_nop 0
	global_load_lds_dwordx4 v101, s[0:1]
	s_add_u32 m0, s8, 0x4000
	s_nop 0
	global_load_lds_dwordx4 v102, s[4:5]
	s_add_u32 m0, s8, 0x5000
	s_nop 0
	global_load_lds_dwordx4 v103, s[4:5]
	s_add_u32 m0, s8, 0x6000
	s_nop 0
	global_load_lds_dwordx4 v104, s[4:5]
	s_add_u32 m0, s8, 0x7000
	s_nop 0
	global_load_lds_dwordx4 v105, s[4:5]
	s_waitcnt vmcnt(0)
	s_add_u32 s0, s0, 0x80
	s_addc_u32 s1, s1, 0
	s_add_u32 s4, s4, 0x80
	s_addc_u32 s5, s5, 0
	s_barrier
	s_add_u32 m0, s8, 0x8000
	ds_read_b128 v[142:145], v106
	ds_read_b128 v[158:161], v108 offset:16384
	s_nop 0
	global_load_lds_dwordx4 v98, s[0:1]
	s_add_u32 m0, s8, 0x9000
	ds_read_b128 v[182:185], v108 offset:18432
	ds_read_b128 v[186:189], v108 offset:20480
	s_nop 0
	global_load_lds_dwordx4 v99, s[0:1]
	s_add_u32 m0, s8, 0xa000
	ds_read_b128 v[206:209], v108 offset:22528
	ds_read_b128 v[146:149], v106 offset:2048
	s_nop 0
	global_load_lds_dwordx4 v100, s[0:1]
	s_add_u32 m0, s8, 0xb000
	ds_read_b128 v[150:153], v106 offset:4096
	ds_read_b128 v[154:157], v106 offset:6144
	s_nop 0
	global_load_lds_dwordx4 v101, s[0:1]
	s_add_u32 m0, s8, 0xc000
	s_nop 0
	global_load_lds_dwordx4 v102, s[4:5]
	s_add_u32 m0, s8, 0xd000
	s_nop 0
	global_load_lds_dwordx4 v103, s[4:5]
	s_add_u32 m0, s8, 0xe000
	s_nop 0
	global_load_lds_dwordx4 v104, s[4:5]
	s_add_u32 m0, s8, 0xf000
	s_nop 0
	global_load_lds_dwordx4 v105, s[4:5]
	s_add_u32 s0, s0, 0x80
	s_addc_u32 s1, s1, 0
	s_add_u32 s4, s4, 0x80
	s_addc_u32 s5, s5, 0
	s_waitcnt lgkmcnt(0)
	v_mfma_f32_16x16x32_bf16 v[94:97], v[158:161], v[142:145], 0
	ds_read_b128 v[50:53], v107
	ds_read_b128 v[66:69], v109 offset:16384
	v_mfma_f32_16x16x32_bf16 v[90:93], v[182:185], v[142:145], 0
	v_mfma_f32_16x16x32_bf16 v[86:89], v[186:189], v[142:145], 0
	ds_read_b128 v[70:73], v109 offset:18432
	ds_read_b128 v[78:81], v109 offset:20480
	v_mfma_f32_16x16x32_bf16 v[74:77], v[206:209], v[142:145], 0
	v_mfma_f32_16x16x32_bf16 v[46:49], v[158:161], v[146:149], 0
	ds_read_b128 v[82:85], v109 offset:22528
	ds_read_b128 v[54:57], v107 offset:2048
	v_mfma_f32_16x16x32_bf16 v[42:45], v[182:185], v[146:149], 0
	v_mfma_f32_16x16x32_bf16 v[38:41], v[186:189], v[146:149], 0
	ds_read_b128 v[58:61], v107 offset:4096
	ds_read_b128 v[62:65], v107 offset:6144
	v_mfma_f32_16x16x32_bf16 v[34:37], v[206:209], v[146:149], 0
	v_mfma_f32_16x16x32_bf16 v[30:33], v[158:161], v[150:153], 0
	v_mfma_f32_16x16x32_bf16 v[26:29], v[182:185], v[150:153], 0
	v_mfma_f32_16x16x32_bf16 v[22:25], v[186:189], v[150:153], 0
	v_mfma_f32_16x16x32_bf16 v[18:21], v[206:209], v[150:153], 0
	v_mfma_f32_16x16x32_bf16 v[14:17], v[158:161], v[154:157], 0
	v_mfma_f32_16x16x32_bf16 v[10:13], v[182:185], v[154:157], 0
	v_mfma_f32_16x16x32_bf16 v[2:5], v[186:189], v[154:157], 0
	v_mfma_f32_16x16x32_bf16 v[6:9], v[206:209], v[154:157], 0
	s_waitcnt vmcnt(0) lgkmcnt(0)
	s_barrier
	s_movk_i32 s9, 7

.LBB0_440:
	v_lshlrev_b32_e32 v0, 4, v4
	v_and_b32_e32 v0, 0xf0, v0
	v_ashrrev_i32_e32 v5, 4, v4
	s_movk_i32 s14, 0x110
	v_mad_u64_u32 v[2:3], s[12:13], v5, s14, v[0:1]
	ds_read_b128 v[6:9], v2
	v_ashrrev_i32_e32 v51, 31, v50
	v_add_u32_e32 v5, v5, v34
	v_mov_b64_e32 v[2:3], s[78:79]
	v_mad_i64_i32 v[10:11], s[12:13], v5, s93, v[2:3]
	v_lshlrev_b64 v[12:13], 1, v[50:51]
	v_lshl_add_u64 v[10:11], v[10:11], 0, v[12:13]
	v_add_u32_e32 v5, 0x100, v4
	v_lshl_add_u64 v[10:11], v[10:11], 0, v[0:1]
	v_ashrrev_i32_e32 v5, 4, v5
	s_waitcnt lgkmcnt(0)
	global_store_dwordx4 v[10:11], v[6:9], off nt
	s_andn2_b64 s[10:11], s[10:11], exec
	s_nop 0
	v_mad_u64_u32 v[6:7], s[12:13], v5, s14, v[0:1]
	ds_read_b128 v[6:9], v6
	v_add_u32_e32 v5, v5, v34
	v_mad_i64_i32 v[10:11], s[12:13], v5, s93, v[2:3]
	v_lshl_add_u64 v[10:11], v[10:11], 0, v[12:13]
	v_add_u32_e32 v5, 0x200, v4
	v_lshl_add_u64 v[10:11], v[10:11], 0, v[0:1]
	v_ashrrev_i32_e32 v5, 4, v5
	s_waitcnt lgkmcnt(0)
	global_store_dwordx4 v[10:11], v[6:9], off nt
	s_nop 1
	v_mad_u64_u32 v[6:7], s[12:13], v5, s14, v[0:1]
	ds_read_b128 v[6:9], v6
	v_add_u32_e32 v5, v5, v34
	v_mad_i64_i32 v[10:11], s[12:13], v5, s93, v[2:3]
	v_lshl_add_u64 v[10:11], v[10:11], 0, v[12:13]
	v_add_u32_e32 v5, 0x300, v4
	v_lshl_add_u64 v[10:11], v[10:11], 0, v[0:1]
	v_ashrrev_i32_e32 v5, 4, v5
	s_waitcnt lgkmcnt(0)
	global_store_dwordx4 v[10:11], v[6:9], off nt
	s_nop 1
	v_mad_u64_u32 v[6:7], s[12:13], v5, s14, v[0:1]
	ds_read_b128 v[6:9], v6
	v_add_u32_e32 v5, v5, v34
	v_mad_i64_i32 v[10:11], s[12:13], v5, s93, v[2:3]
	v_lshl_add_u64 v[10:11], v[10:11], 0, v[12:13]
	v_add_u32_e32 v5, 0x400, v4
	v_lshl_add_u64 v[10:11], v[10:11], 0, v[0:1]
	v_ashrrev_i32_e32 v5, 4, v5
	s_waitcnt lgkmcnt(0)
	global_store_dwordx4 v[10:11], v[6:9], off nt
	s_nop 1
	v_mad_u64_u32 v[6:7], s[12:13], v5, s14, v[0:1]
	ds_read_b128 v[6:9], v6
	v_add_u32_e32 v5, v5, v34
	v_mad_i64_i32 v[10:11], s[12:13], v5, s93, v[2:3]
	v_lshl_add_u64 v[10:11], v[10:11], 0, v[12:13]
	v_add_u32_e32 v5, 0x500, v4
	v_lshl_add_u64 v[10:11], v[10:11], 0, v[0:1]
	v_ashrrev_i32_e32 v5, 4, v5
	s_waitcnt lgkmcnt(0)
	global_store_dwordx4 v[10:11], v[6:9], off nt
	s_nop 1
	v_mad_u64_u32 v[6:7], s[12:13], v5, s14, v[0:1]
	ds_read_b128 v[6:9], v6
	v_add_u32_e32 v5, v5, v34
	v_mad_i64_i32 v[10:11], s[12:13], v5, s93, v[2:3]
	v_lshl_add_u64 v[10:11], v[10:11], 0, v[12:13]
	v_add_u32_e32 v5, 0x600, v4
	v_lshl_add_u64 v[10:11], v[10:11], 0, v[0:1]
	v_ashrrev_i32_e32 v5, 4, v5
	s_waitcnt lgkmcnt(0)
	global_store_dwordx4 v[10:11], v[6:9], off nt
	s_nop 1
	v_mad_u64_u32 v[6:7], s[12:13], v5, s14, v[0:1]
	ds_read_b128 v[6:9], v6
	v_add_u32_e32 v5, v5, v34
	v_mad_i64_i32 v[10:11], s[12:13], v5, s93, v[2:3]
	v_lshl_add_u64 v[10:11], v[10:11], 0, v[12:13]
	v_add_u32_e32 v5, 0x700, v4
	v_lshl_add_u64 v[10:11], v[10:11], 0, v[0:1]
	v_ashrrev_i32_e32 v5, 4, v5
	s_waitcnt lgkmcnt(0)
	global_store_dwordx4 v[10:11], v[6:9], off nt
	s_nop 1
	v_mad_u64_u32 v[6:7], s[12:13], v5, s14, v[0:1]
	ds_read_b128 v[6:9], v6
	v_add_u32_e32 v5, v5, v34
	v_mad_i64_i32 v[2:3], s[12:13], v5, s93, v[2:3]
	v_lshl_add_u64 v[2:3], v[2:3], 0, v[12:13]
	v_lshl_add_u64 v[2:3], v[2:3], 0, v[0:1]
	s_waitcnt lgkmcnt(0)
	global_store_dwordx4 v[2:3], v[6:9], off nt
